# v68 = v63 with packed f32 ops in the past PV MFMA stretch split into scalar pairs (7.5 packed-vs-scalar lever, bit-identical)
# speedup vs baseline: 1.0017x; 1.0017x over previous
.LBB0_259:
	ds_read_b128 v[72:75], v116 offset:64
	ds_read_b128 v[100:103], v116 offset:2368
	v_mov_b32_e32 v163, v164
	v_add_u32_e32 v164, s0, v121
	s_waitcnt lgkmcnt(2)
	v_mfma_f32_16x16x32_bf16 v[198:201], v[234:237], v[40:43], 0
	v_mov_b32_e32 v165, v166
	v_add_u32_e32 v166, 0x2000, v164
	v_add_u32_e32 v167, 0x4000, v164
	v_mfma_f32_16x16x32_bf16 v[104:107], v[234:237], v[36:39], 0
	ds_read_b128 v[80:83], v116 offset:4608
	ds_read_b128 v[76:79], v116 offset:4672
	s_addk_i32 s0, 0x80
	s_cmpk_eq_i32 s0, 0x200
	v_mfma_f32_16x16x32_bf16 v[68:71], v[238:241], v[40:43], 0
	v_mfma_f32_16x16x32_bf16 v[64:67], v[238:241], v[36:39], 0
	s_waitcnt lgkmcnt(1)
	v_mfma_f32_16x16x32_bf16 v[92:95], v[80:83], v[40:43], 0
	v_mfma_f32_16x16x32_bf16 v[84:87], v[80:83], v[36:39], 0
	ds_read_b128 v[88:91], v116 offset:6912
	ds_read_b128 v[80:83], v116 offset:6976
	v_add_u32_e32 v116, 0x2400, v116
	s_waitcnt lgkmcnt(1)
	v_mfma_f32_16x16x32_bf16 v[96:99], v[88:91], v[40:43], 0
	v_mfma_f32_16x16x32_bf16 v[88:91], v[88:91], v[36:39], 0
	v_mfma_f32_16x16x32_bf16 v[68:71], v[72:75], v[44:47], v[68:71]
	v_mfma_f32_16x16x32_bf16 v[72:75], v[72:75], v[32:35], v[64:67]
	v_mfma_f32_16x16x32_bf16 v[64:67], v[100:103], v[44:47], v[198:201]
	v_mfma_f32_16x16x32_bf16 v[100:103], v[100:103], v[32:35], v[104:107]
	s_nop 2
	ds_read2_b64 v[104:107], v164 offset1:4
	ds_read2_b64 v[198:201], v164 offset0:8 offset1:12
	v_add_u32_e32 v164, 0x6000, v164
	v_mfma_f32_16x16x32_bf16 v[92:95], v[76:79], v[44:47], v[92:95]
	v_mfma_f32_16x16x32_bf16 v[76:79], v[76:79], v[32:35], v[84:87]
	s_nop 2
	ds_read2_b64 v[84:87], v166 offset0:32 offset1:36
	ds_read2_b64 v[202:205], v166 offset0:40 offset1:44
	ds_read2_b64 v[206:209], v167 offset0:64 offset1:68
	ds_read2_b64 v[210:213], v167 offset0:72 offset1:76
	ds_read2_b64 v[214:217], v164 offset0:96 offset1:100
	ds_read2_b64 v[218:221], v164 offset0:104 offset1:108
	s_waitcnt lgkmcnt(8)
	v_mfma_f32_16x16x32_bf16 v[96:99], v[80:83], v[44:47], v[96:99]
	v_mfma_f32_16x16x32_bf16 v[80:83], v[80:83], v[32:35], v[88:91]
	s_nop 2
	v_max3_f32 v88, v68, s4, v69
	v_max3_f32 v89, v72, s4, v73
	v_max3_f32 v88, v88, v70, v71
	v_max3_f32 v89, v89, v74, v75
	v_max3_f32 v88, v88, v64, v65
	v_max3_f32 v89, v89, v100, v101
	v_max3_f32 v88, v88, v66, v67
	v_max3_f32 v89, v89, v102, v103
	v_max3_f32 v88, v88, v92, v93
	v_max3_f32 v89, v89, v76, v77
	v_max3_f32 v88, v88, v94, v95
	v_max3_f32 v89, v89, v78, v79
	v_max3_f32 v88, v88, v96, v97
	v_max3_f32 v89, v89, v80, v81
	v_max3_f32 v88, v88, v98, v99
	v_max3_f32 v89, v89, v82, v83
	v_mov_b32_e32 v90, v88
	v_mov_b32_e32 v91, v89
	s_nop 0
	v_permlane16_swap_b32_e32 v90, v88
	v_permlane16_swap_b32_e32 v91, v89
	v_max_f32_e32 v88, v88, v90
	v_max_f32_e32 v89, v89, v91
	v_mov_b32_e32 v90, v88
	v_mov_b32_e32 v91, v89
	s_nop 0
	v_permlane32_swap_b32_e32 v90, v88
	v_permlane32_swap_b32_e32 v91, v89
	v_max3_f32 v164, v163, v89, v91
	v_max3_f32 v166, v165, v88, v90
	v_sub_f32_e32 v89, v163, v164
	v_sub_f32_e32 v88, v165, v166
	v_sub_f32_e32 v90, 0, v166
	v_sub_f32_e32 v178, 0, v164
	v_pk_add_f32 v[68:69], v[68:69], v[90:91] op_sel_hi:[1,0]
	v_pk_add_f32 v[70:71], v[70:71], v[90:91] op_sel_hi:[1,0]
	v_pk_add_f32 v[72:73], v[72:73], v[178:179] op_sel_hi:[1,0]
	v_pk_add_f32 v[74:75], v[74:75], v[178:179] op_sel_hi:[1,0]
	v_exp_f32_e32 v88, v88
	v_exp_f32_e32 v89, v89
	v_pk_add_f32 v[64:65], v[64:65], v[90:91] op_sel_hi:[1,0]
	v_pk_add_f32 v[66:67], v[66:67], v[90:91] op_sel_hi:[1,0]
	v_mov_b32_e32 v186, v89
	v_exp_f32_e32 v68, v68
	v_exp_f32_e32 v69, v69
	v_exp_f32_e32 v70, v70
	v_exp_f32_e32 v71, v71
	v_pk_add_f32 v[100:101], v[100:101], v[178:179] op_sel_hi:[1,0]
	v_pk_add_f32 v[102:103], v[102:103], v[178:179] op_sel_hi:[1,0]
	v_exp_f32_e32 v72, v72
	v_exp_f32_e32 v73, v73
	v_exp_f32_e32 v74, v74
	v_exp_f32_e32 v75, v75
	v_pk_mul_f32 v[60:61], v[60:61], v[88:89] op_sel_hi:[1,0]
	v_pk_mul_f32 v[62:63], v[62:63], v[88:89] op_sel_hi:[1,0]
	v_exp_f32_e32 v64, v64
	v_exp_f32_e32 v65, v65
	v_exp_f32_e32 v66, v66
	v_exp_f32_e32 v67, v67
	v_pk_mul_f32 v[56:57], v[56:57], v[88:89] op_sel_hi:[1,0]
	v_pk_mul_f32 v[58:59], v[58:59], v[88:89] op_sel_hi:[1,0]
	v_exp_f32_e32 v100, v100
	v_exp_f32_e32 v101, v101
	v_exp_f32_e32 v102, v102
	v_exp_f32_e32 v103, v103
	v_cvt_pk_bf16_f32 v222, v68, v69
	v_cvt_pk_bf16_f32 v223, v70, v71
	v_cvt_pk_bf16_f32 v224, v64, v65
	v_cvt_pk_bf16_f32 v225, v66, v67
	v_mul_f32_e32 v28, v28, v186
	v_mul_f32_e32 v29, v29, v186
	v_mul_f32_e32 v30, v30, v186
	v_mul_f32_e32 v31, v31, v186
	s_waitcnt lgkmcnt(7)
	v_mfma_f32_16x16x32_bf16 v[60:63], v[104:107], v[222:225], v[60:63]
	v_cvt_pk_bf16_f32 v226, v72, v73
	v_cvt_pk_bf16_f32 v227, v74, v75
	s_waitcnt lgkmcnt(5)
	v_mfma_f32_16x16x32_bf16 v[56:59], v[84:87], v[222:225], v[56:59]
	v_cvt_pk_bf16_f32 v228, v100, v101
	v_cvt_pk_bf16_f32 v229, v102, v103
	v_mul_f32_e32 v24, v24, v186
	v_mul_f32_e32 v25, v25, v186
	v_mul_f32_e32 v26, v26, v186
	v_mul_f32_e32 v27, v27, v186
	s_nop 1
	v_mfma_f32_16x16x32_bf16 v[28:31], v[104:107], v[226:229], v[28:31]
	v_add_f32_e32 v92, v92, v90
	v_add_f32_e32 v93, v93, v90
	v_add_f32_e32 v94, v94, v90
	v_add_f32_e32 v95, v95, v90
	v_mul_f32_e32 v52, v52, v88
	v_mul_f32_e32 v53, v53, v88
	v_mul_f32_e32 v54, v54, v88
	v_mul_f32_e32 v55, v55, v88
	v_mfma_f32_16x16x32_bf16 v[24:27], v[84:87], v[226:229], v[24:27]
	v_add_f32_e32 v96, v96, v90
	v_add_f32_e32 v97, v97, v90
	v_add_f32_e32 v98, v98, v90
	v_add_f32_e32 v99, v99, v90
	v_mul_f32_e32 v48, v48, v88
	v_mul_f32_e32 v49, v49, v88
	v_mul_f32_e32 v50, v50, v88
	v_mul_f32_e32 v51, v51, v88
	s_waitcnt lgkmcnt(3)
	v_mfma_f32_16x16x32_bf16 v[52:55], v[206:209], v[222:225], v[52:55]
	v_exp_f32_e32 v92, v92
	v_exp_f32_e32 v93, v93
	v_exp_f32_e32 v94, v94
	v_exp_f32_e32 v95, v95
	s_waitcnt lgkmcnt(1)
	v_mfma_f32_16x16x32_bf16 v[48:51], v[214:217], v[222:225], v[48:51]
	v_exp_f32_e32 v96, v96
	v_exp_f32_e32 v97, v97
	v_exp_f32_e32 v98, v98
	v_exp_f32_e32 v99, v99
	v_add_f32_e32 v76, v76, v178
	v_add_f32_e32 v77, v77, v178
	v_add_f32_e32 v78, v78, v178
	v_add_f32_e32 v79, v79, v178
	v_add_f32_e32 v80, v80, v178
	v_add_f32_e32 v81, v81, v178
	v_add_f32_e32 v82, v82, v178
	v_add_f32_e32 v83, v83, v178
	v_cvt_pk_bf16_f32 v222, v92, v93
	v_cvt_pk_bf16_f32 v223, v94, v95
	v_cvt_pk_bf16_f32 v224, v96, v97
	v_cvt_pk_bf16_f32 v225, v98, v99
	v_exp_f32_e32 v76, v76
	v_exp_f32_e32 v77, v77
	s_nop 1
	v_mfma_f32_16x16x32_bf16 v[60:63], v[198:201], v[222:225], v[60:63]
	v_exp_f32_e32 v78, v78
	v_exp_f32_e32 v79, v79
	v_mfma_f32_16x16x32_bf16 v[56:59], v[202:205], v[222:225], v[56:59]
	v_exp_f32_e32 v80, v80
	v_exp_f32_e32 v81, v81
	v_mfma_f32_16x16x32_bf16 v[52:55], v[210:213], v[222:225], v[52:55]
	v_exp_f32_e32 v82, v82
	v_exp_f32_e32 v83, v83
	s_waitcnt lgkmcnt(0)
	v_mfma_f32_16x16x32_bf16 v[48:51], v[218:221], v[222:225], v[48:51]
	ds_read_b128 v[234:237], v116 offset:2304
	ds_read_b128 v[238:241], v116
	v_mul_f32_e32 v20, v20, v186
	v_mul_f32_e32 v21, v21, v186
	v_mul_f32_e32 v22, v22, v186
	v_mul_f32_e32 v23, v23, v186
	v_mul_f32_e32 v16, v16, v186
	v_mul_f32_e32 v17, v17, v186
	v_mul_f32_e32 v18, v18, v186
	v_mul_f32_e32 v19, v19, v186
	s_nop 1
	v_mfma_f32_16x16x32_bf16 v[20:23], v[206:209], v[226:229], v[20:23]
	v_add_f32_e32 v90, v68, v70
	v_add_f32_e32 v91, v69, v71
	v_add_f32_e32 v178, v72, v74
	v_add_f32_e32 v179, v73, v75
	v_mfma_f32_16x16x32_bf16 v[16:19], v[214:217], v[226:229], v[16:19]
	v_cvt_pk_bf16_f32 v226, v76, v77
	v_cvt_pk_bf16_f32 v227, v78, v79
	v_cvt_pk_bf16_f32 v228, v80, v81
	v_cvt_pk_bf16_f32 v229, v82, v83
	v_add_f32_e32 v90, v90, v64
	v_add_f32_e32 v91, v91, v65
	v_add_f32_e32 v178, v178, v100
	v_add_f32_e32 v179, v179, v101
	s_nop 1
	v_mfma_f32_16x16x32_bf16 v[28:31], v[198:201], v[226:229], v[28:31]
	v_add_f32_e32 v90, v90, v66
	v_add_f32_e32 v91, v91, v67
	v_add_f32_e32 v178, v178, v102
	v_add_f32_e32 v179, v179, v103
	v_mfma_f32_16x16x32_bf16 v[24:27], v[202:205], v[226:229], v[24:27]
	v_add_f32_e32 v90, v90, v92
	v_add_f32_e32 v91, v91, v93
	v_add_f32_e32 v178, v178, v76
	v_add_f32_e32 v179, v179, v77
	v_mfma_f32_16x16x32_bf16 v[20:23], v[210:213], v[226:229], v[20:23]
	v_add_f32_e32 v90, v90, v94
	v_add_f32_e32 v91, v91, v95
	v_add_f32_e32 v178, v178, v78
	v_add_f32_e32 v179, v179, v79
	v_mfma_f32_16x16x32_bf16 v[16:19], v[218:221], v[226:229], v[16:19]
	v_add_f32_e32 v90, v90, v96
	v_add_f32_e32 v91, v91, v97
	v_add_f32_e32 v178, v178, v80
	v_add_f32_e32 v179, v179, v81
	v_add_f32_e32 v90, v90, v98
	v_add_f32_e32 v91, v91, v99
	v_add_f32_e32 v178, v178, v82
	v_add_f32_e32 v179, v179, v83
	v_add_f32_e32 v64, v90, v91
	v_add_f32_e32 v65, v178, v179
	v_mov_b32_e32 v66, v64
	v_mov_b32_e32 v67, v65
	s_nop 0
	v_permlane16_swap_b32_e32 v66, v64
	v_permlane16_swap_b32_e32 v67, v65
	v_add_f32_e32 v64, v64, v66
	v_add_f32_e32 v65, v65, v67
	s_nop 0
	v_mov_b32_e32 v66, v64
	v_mov_b32_e32 v67, v65
	s_nop 0
	v_permlane32_swap_b32_e32 v66, v64
	v_permlane32_swap_b32_e32 v67, v65
	v_add_f32_e32 v64, v64, v66
	v_add_f32_e32 v65, v65, v67
	s_nop 0
	v_fma_f32 v158, v158, v88, v64
	v_fma_f32 v159, v159, v89, v65
	s_cmpk_lg_i32 s0, 0x80
	s_cbranch_scc1 .Lpast_qskip
	s_cmp_lg_u64 s[22:23], 0
	s_cbranch_scc1 .Lpast_qskip
	v_mov_b32_e32 v233, 0
	s_waitcnt vmcnt(1)
	v_and_b32_e32 v137, 0xfff, v141
	v_lshlrev_b32_e32 v232, 7, v137
	v_lshl_add_u64 v[4:5], v[156:157], 0, v[232:233]
	global_load_dwordx4 v[0:3], v[4:5], off
	s_nop 0
	global_load_dwordx4 v[4:7], v[4:5], off offset:64
	s_waitcnt vmcnt(2)
	v_and_b32_e32 v139, 0xfff, v149
	v_lshlrev_b32_e32 v232, 7, v139
	v_lshl_add_u64 v[12:13], v[156:157], 0, v[232:233]
	global_load_dwordx4 v[8:11], v[12:13], off
	s_nop 0
	global_load_dwordx4 v[12:15], v[12:13], off offset:64
